# phase 3: half of the workgroups run conv/pool before attention (memory-bound and VALU-bound halves overlap across CUs)
# speedup vs baseline: 1.0064x; 1.0064x over previous
.LBB0_317:
	s_andn2_b64 vcc, exec, s[2:3]
	s_cbranch_vccnz .LBB0_403
	s_mov_b32 s100, 0
	v_readlane_b32 s0, v253, 0
	s_bitcmp1_b32 s0, 3
	s_cbranch_scc0 .Lsw_attn
	s_mov_b32 s100, 1
	s_branch .LBB0_360
.Lsw_attn:
	v_readlane_b32 s0, v253, 0
	s_cmpk_gt_i32 s0, 0xff
	s_cbranch_scc1 .Lsw_atx
	s_lshl_b32 s1, s82, 3
	s_add_u32 s14, s4, 0x1000
	s_addc_u32 s15, s5, 0
	s_lshl_b32 s42, s0, 1
	s_branch .LBB0_321

.Lsw_atx:
	s_cmp_eq_u32 s100, 2
	s_cbranch_scc1 .LBB0_403
	s_branch .LBB0_360
.Lsw_cpx:
	s_cmp_eq_u32 s100, 1
	s_cbranch_scc0 .LBB0_403
	s_mov_b32 s100, 2
	s_branch .Lsw_attn
